# grid barrier poll loop: 512-cycle pause between polls of the top-level counter instead of 64
# speedup vs baseline: 1.0034x; 1.0034x over previous
.Lgb1_poll:
	global_load_dword v3, v1, s[2:3] sc1
	s_waitcnt vmcnt(0)
	v_readfirstlane_b32 s13, v3
	s_nop 0
	s_cmp_ge_u32 s13, s12
	s_cbranch_scc1 .Lgb1_done
	s_sleep 8
	s_branch .Lgb1_poll
